# pool prep: 24-row register window per 8 output rows (all row loads issued up front), rstd pre-pass with 8 loads in flight; same arithmetic order as before
# speedup vs baseline: 1.0217x; 1.0041x over previous
.LBB0_600:
	v_add_u32_e32 v6, s4, v4
	v_cmp_gt_u32_e32 vcc, s33, v6
	s_and_saveexec_b64 s[48:49], vcc
	s_cbranch_execz .LBB0_599
	v_lshl_add_u64 v[10:11], v[0:1], 2, v[2:3]
	global_load_dwordx4 v[100:103], v[10:11], off
	global_load_dwordx4 v[104:107], v[10:11], off offset:1024
	global_load_dwordx4 v[108:111], v[10:11], off offset:2048
	global_load_dwordx4 v[112:115], v[10:11], off offset:3072
	v_add_co_u32_e32 v10, vcc, s33, v10
	s_nop 1
	v_addc_co_u32_e32 v11, vcc, 0, v11, vcc
	global_load_dwordx4 v[116:119], v[10:11], off
	global_load_dwordx4 v[120:123], v[10:11], off offset:1024
	global_load_dwordx4 v[124:127], v[10:11], off offset:2048
	global_load_dwordx4 v[128:131], v[10:11], off offset:3072
	s_waitcnt vmcnt(7)
	v_mul_f32_e32 v7, v101, v101
	v_fmac_f32_e32 v7, v100, v100
	v_mul_f32_e32 v6, v103, v103
	v_fmac_f32_e32 v6, v102, v102
	v_add_f32_e32 v20, v7, v6
	s_waitcnt vmcnt(6)
	v_mul_f32_e32 v7, v105, v105
	v_fmac_f32_e32 v7, v104, v104
	v_mul_f32_e32 v6, v107, v107
	v_fmac_f32_e32 v6, v106, v106
	v_add_f32_e32 v6, v7, v6
	v_add_f32_e32 v20, v20, v6
	s_waitcnt vmcnt(5)
	v_mul_f32_e32 v7, v109, v109
	v_fmac_f32_e32 v7, v108, v108
	v_mul_f32_e32 v6, v111, v111
	v_fmac_f32_e32 v6, v110, v110
	v_add_f32_e32 v6, v7, v6
	v_add_f32_e32 v20, v20, v6
	s_waitcnt vmcnt(4)
	v_mul_f32_e32 v7, v113, v113
	v_fmac_f32_e32 v7, v112, v112
	v_mul_f32_e32 v6, v115, v115
	v_fmac_f32_e32 v6, v114, v114
	v_add_f32_e32 v6, v7, v6
	v_add_f32_e32 v20, v20, v6
	s_waitcnt vmcnt(3)
	v_mul_f32_e32 v7, v117, v117
	v_fmac_f32_e32 v7, v116, v116
	v_mul_f32_e32 v6, v119, v119
	v_fmac_f32_e32 v6, v118, v118
	v_add_f32_e32 v6, v7, v6
	v_add_f32_e32 v20, v20, v6
	s_waitcnt vmcnt(2)
	v_mul_f32_e32 v7, v121, v121
	v_fmac_f32_e32 v7, v120, v120
	v_mul_f32_e32 v6, v123, v123
	v_fmac_f32_e32 v6, v122, v122
	v_add_f32_e32 v6, v7, v6
	v_add_f32_e32 v20, v20, v6
	s_waitcnt vmcnt(1)
	v_mul_f32_e32 v7, v125, v125
	v_fmac_f32_e32 v7, v124, v124
	v_mul_f32_e32 v6, v127, v127
	v_fmac_f32_e32 v6, v126, v126
	v_add_f32_e32 v6, v7, v6
	v_add_f32_e32 v20, v20, v6
	s_waitcnt vmcnt(0)
	v_mul_f32_e32 v7, v129, v129
	v_fmac_f32_e32 v7, v128, v128
	v_mul_f32_e32 v6, v131, v131
	v_fmac_f32_e32 v6, v130, v130
	v_add_f32_e32 v6, v7, v6
	v_add_f32_e32 v6, v20, v6
	s_nop 1
	v_add_f32_dpp v6, v6, v6 quad_perm:[1,0,3,2] row_mask:0xf bank_mask:0xf bound_ctrl:1
	s_nop 1
	v_add_f32_dpp v6, v6, v6 quad_perm:[2,3,0,1] row_mask:0xf bank_mask:0xf bound_ctrl:1
	s_nop 1
	v_add_f32_dpp v6, v6, v6 row_half_mirror row_mask:0xf bank_mask:0xf bound_ctrl:1
	s_nop 1
	v_add_f32_dpp v6, v6, v6 row_mirror row_mask:0xf bank_mask:0xf bound_ctrl:1
	s_nop 0
	v_readlane_b32 s50, v6, 0
	v_readlane_b32 s5, v6, 16
	v_readlane_b32 s51, v6, 32
	v_readlane_b32 s53, v6, 48
	s_and_b64 exec, exec, s[42:43]
	s_cbranch_execz .LBB0_599
	v_mov_b32_e32 v6, s5
	v_mov_b32_e32 v7, s53
	v_pk_add_f32 v[6:7], s[50:51], v[6:7]
	s_nop 0
	v_add_f32_e32 v6, v6, v7
	v_fmamk_f32 v6, v6, 0x3a000000, v236
	v_mul_f32_e32 v7, 0x4b800000, v6
	v_cmp_gt_f32_e32 vcc, s13, v6
	s_nop 1
	v_cndmask_b32_e32 v6, v6, v7, vcc
	v_rsq_f32_e32 v6, v6
	s_nop 0
	v_mul_f32_e32 v7, 0x45800000, v6
	v_cndmask_b32_e32 v6, v6, v7, vcc
	ds_write_b32 v5, v6
	s_branch .LBB0_599

.LBB0_604:
	s_or_b64 exec, exec, s[8:9]
	s_waitcnt lgkmcnt(0)
	s_barrier
	global_load_dwordx4 v[4:7], v[14:15], off
	v_readfirstlane_b32 s100, v47
	v_lshl_add_u64 v[2:3], v[16:17], 0, v[40:41]
	v_lshlrev_b64 v[22:23], 24, v[22:23]
	s_ashr_i32 s5, s4, 31
	s_lshl_b64 s[6:7], s[4:5], 12
	v_lshl_add_u64 v[22:23], v[22:23], 0, s[6:7]
	v_lshl_add_u64 v[22:23], v[18:19], 0, v[22:23]
	v_add_co_u32_e32 v22, vcc, 0xffff9000, v22
	s_nop 1
	v_addc_co_u32_e32 v23, vcc, -1, v23, vcc
	v_mov_b32_e32 v8, 0
	v_mov_b32_e32 v9, 0
	v_mov_b32_e32 v10, 0
	v_mov_b32_e32 v11, 0
	s_mov_b64 s[48:49], 0x1000
	s_mov_b32 s5, 0
.Lpp_blk:
	s_mov_b32 s9, 0
	s_lshl_b32 s6, s5, 3
	s_add_i32 s6, s6, s4
	s_add_i32 s6, s6, -8
	s_add_i32 s7, s6, 0
	s_max_i32 s7, s7, 0
	s_min_i32 s7, s7, 0xfff
	s_lshl_b32 s8, s7, 13
	v_lshl_add_u64 v[224:225], v[2:3], 0, s[8:9]
	global_load_dwordx4 v[94:97], v[224:225], off
	s_add_i32 s7, s6, 1
	s_max_i32 s7, s7, 0
	s_min_i32 s7, s7, 0xfff
	s_lshl_b32 s8, s7, 13
	v_lshl_add_u64 v[224:225], v[2:3], 0, s[8:9]
	global_load_dwordx4 v[98:101], v[224:225], off
	s_add_i32 s7, s6, 2
	s_max_i32 s7, s7, 0
	s_min_i32 s7, s7, 0xfff
	s_lshl_b32 s8, s7, 13
	v_lshl_add_u64 v[224:225], v[2:3], 0, s[8:9]
	global_load_dwordx4 v[102:105], v[224:225], off
	s_add_i32 s7, s6, 3
	s_max_i32 s7, s7, 0
	s_min_i32 s7, s7, 0xfff
	s_lshl_b32 s8, s7, 13
	v_lshl_add_u64 v[224:225], v[2:3], 0, s[8:9]
	global_load_dwordx4 v[106:109], v[224:225], off
	s_add_i32 s7, s6, 4
	s_max_i32 s7, s7, 0
	s_min_i32 s7, s7, 0xfff
	s_lshl_b32 s8, s7, 13
	v_lshl_add_u64 v[224:225], v[2:3], 0, s[8:9]
	global_load_dwordx4 v[110:113], v[224:225], off
	s_add_i32 s7, s6, 5
	s_max_i32 s7, s7, 0
	s_min_i32 s7, s7, 0xfff
	s_lshl_b32 s8, s7, 13
	v_lshl_add_u64 v[224:225], v[2:3], 0, s[8:9]
	global_load_dwordx4 v[114:117], v[224:225], off
	s_add_i32 s7, s6, 6
	s_max_i32 s7, s7, 0
	s_min_i32 s7, s7, 0xfff
	s_lshl_b32 s8, s7, 13
	v_lshl_add_u64 v[224:225], v[2:3], 0, s[8:9]
	global_load_dwordx4 v[118:121], v[224:225], off
	s_add_i32 s7, s6, 7
	s_max_i32 s7, s7, 0
	s_min_i32 s7, s7, 0xfff
	s_lshl_b32 s8, s7, 13
	v_lshl_add_u64 v[224:225], v[2:3], 0, s[8:9]
	global_load_dwordx4 v[122:125], v[224:225], off
	s_add_i32 s7, s6, 8
	s_max_i32 s7, s7, 0
	s_min_i32 s7, s7, 0xfff
	s_lshl_b32 s8, s7, 13
	v_lshl_add_u64 v[224:225], v[2:3], 0, s[8:9]
	global_load_dwordx4 v[126:129], v[224:225], off
	s_add_i32 s7, s6, 9
	s_max_i32 s7, s7, 0
	s_min_i32 s7, s7, 0xfff
	s_lshl_b32 s8, s7, 13
	v_lshl_add_u64 v[224:225], v[2:3], 0, s[8:9]
	global_load_dwordx4 v[130:133], v[224:225], off
	s_add_i32 s7, s6, 10
	s_max_i32 s7, s7, 0
	s_min_i32 s7, s7, 0xfff
	s_lshl_b32 s8, s7, 13
	v_lshl_add_u64 v[224:225], v[2:3], 0, s[8:9]
	global_load_dwordx4 v[134:137], v[224:225], off
	s_add_i32 s7, s6, 11
	s_max_i32 s7, s7, 0
	s_min_i32 s7, s7, 0xfff
	s_lshl_b32 s8, s7, 13
	v_lshl_add_u64 v[224:225], v[2:3], 0, s[8:9]
	global_load_dwordx4 v[138:141], v[224:225], off
	s_add_i32 s7, s6, 12
	s_max_i32 s7, s7, 0
	s_min_i32 s7, s7, 0xfff
	s_lshl_b32 s8, s7, 13
	v_lshl_add_u64 v[224:225], v[2:3], 0, s[8:9]
	global_load_dwordx4 v[142:145], v[224:225], off
	s_add_i32 s7, s6, 13
	s_max_i32 s7, s7, 0
	s_min_i32 s7, s7, 0xfff
	s_lshl_b32 s8, s7, 13
	v_lshl_add_u64 v[224:225], v[2:3], 0, s[8:9]
	global_load_dwordx4 v[148:151], v[224:225], off
	s_add_i32 s7, s6, 14
	s_max_i32 s7, s7, 0
	s_min_i32 s7, s7, 0xfff
	s_lshl_b32 s8, s7, 13
	v_lshl_add_u64 v[224:225], v[2:3], 0, s[8:9]
	global_load_dwordx4 v[152:155], v[224:225], off
	s_add_i32 s7, s6, 15
	s_max_i32 s7, s7, 0
	s_min_i32 s7, s7, 0xfff
	s_lshl_b32 s8, s7, 13
	v_lshl_add_u64 v[224:225], v[2:3], 0, s[8:9]
	global_load_dwordx4 v[156:159], v[224:225], off
	s_add_i32 s7, s6, 16
	s_max_i32 s7, s7, 0
	s_min_i32 s7, s7, 0xfff
	s_lshl_b32 s8, s7, 13
	v_lshl_add_u64 v[224:225], v[2:3], 0, s[8:9]
	global_load_dwordx4 v[160:163], v[224:225], off
	s_add_i32 s7, s6, 17
	s_max_i32 s7, s7, 0
	s_min_i32 s7, s7, 0xfff
	s_lshl_b32 s8, s7, 13
	v_lshl_add_u64 v[224:225], v[2:3], 0, s[8:9]
	global_load_dwordx4 v[164:167], v[224:225], off
	s_add_i32 s7, s6, 18
	s_max_i32 s7, s7, 0
	s_min_i32 s7, s7, 0xfff
	s_lshl_b32 s8, s7, 13
	v_lshl_add_u64 v[224:225], v[2:3], 0, s[8:9]
	global_load_dwordx4 v[168:171], v[224:225], off
	s_add_i32 s7, s6, 19
	s_max_i32 s7, s7, 0
	s_min_i32 s7, s7, 0xfff
	s_lshl_b32 s8, s7, 13
	v_lshl_add_u64 v[224:225], v[2:3], 0, s[8:9]
	global_load_dwordx4 v[172:175], v[224:225], off
	s_add_i32 s7, s6, 20
	s_max_i32 s7, s7, 0
	s_min_i32 s7, s7, 0xfff
	s_lshl_b32 s8, s7, 13
	v_lshl_add_u64 v[224:225], v[2:3], 0, s[8:9]
	global_load_dwordx4 v[176:179], v[224:225], off
	s_add_i32 s7, s6, 21
	s_max_i32 s7, s7, 0
	s_min_i32 s7, s7, 0xfff
	s_lshl_b32 s8, s7, 13
	v_lshl_add_u64 v[224:225], v[2:3], 0, s[8:9]
	global_load_dwordx4 v[180:183], v[224:225], off
	s_add_i32 s7, s6, 22
	s_max_i32 s7, s7, 0
	s_min_i32 s7, s7, 0xfff
	s_lshl_b32 s8, s7, 13
	v_lshl_add_u64 v[224:225], v[2:3], 0, s[8:9]
	global_load_dwordx4 v[184:187], v[224:225], off
	s_add_i32 s7, s6, 23
	s_max_i32 s7, s7, 0
	s_min_i32 s7, s7, 0xfff
	s_lshl_b32 s8, s7, 13
	v_lshl_add_u64 v[224:225], v[2:3], 0, s[8:9]
	global_load_dwordx4 v[188:191], v[224:225], off
	s_lshl_b32 s7, s5, 5
	v_mov_b32_e32 v223, s7
	ds_read_b128 v[192:195], v223
	ds_read_b128 v[196:199], v223 offset:16
	ds_read_b128 v[200:203], v223 offset:32
	ds_read_b128 v[204:207], v223 offset:48
	ds_read_b128 v[208:211], v223 offset:64
	ds_read_b128 v[212:215], v223 offset:80
	s_waitcnt lgkmcnt(0)
	s_add_i32 s7, s6, 0
	s_cmp_lt_u32 s7, 0x1000
	s_cselect_b64 vcc, -1, 0
	v_cndmask_b32_e32 v192, 0, v192, vcc
	s_add_i32 s7, s6, 1
	s_cmp_lt_u32 s7, 0x1000
	s_cselect_b64 vcc, -1, 0
	v_cndmask_b32_e32 v193, 0, v193, vcc
	s_add_i32 s7, s6, 2
	s_cmp_lt_u32 s7, 0x1000
	s_cselect_b64 vcc, -1, 0
	v_cndmask_b32_e32 v194, 0, v194, vcc
	s_add_i32 s7, s6, 3
	s_cmp_lt_u32 s7, 0x1000
	s_cselect_b64 vcc, -1, 0
	v_cndmask_b32_e32 v195, 0, v195, vcc
	s_add_i32 s7, s6, 4
	s_cmp_lt_u32 s7, 0x1000
	s_cselect_b64 vcc, -1, 0
	v_cndmask_b32_e32 v196, 0, v196, vcc
	s_add_i32 s7, s6, 5
	s_cmp_lt_u32 s7, 0x1000
	s_cselect_b64 vcc, -1, 0
	v_cndmask_b32_e32 v197, 0, v197, vcc
	s_add_i32 s7, s6, 6
	s_cmp_lt_u32 s7, 0x1000
	s_cselect_b64 vcc, -1, 0
	v_cndmask_b32_e32 v198, 0, v198, vcc
	s_add_i32 s7, s6, 7
	s_cmp_lt_u32 s7, 0x1000
	s_cselect_b64 vcc, -1, 0
	v_cndmask_b32_e32 v199, 0, v199, vcc
	s_add_i32 s7, s6, 8
	s_cmp_lt_u32 s7, 0x1000
	s_cselect_b64 vcc, -1, 0
	v_cndmask_b32_e32 v200, 0, v200, vcc
	s_add_i32 s7, s6, 9
	s_cmp_lt_u32 s7, 0x1000
	s_cselect_b64 vcc, -1, 0
	v_cndmask_b32_e32 v201, 0, v201, vcc
	s_add_i32 s7, s6, 10
	s_cmp_lt_u32 s7, 0x1000
	s_cselect_b64 vcc, -1, 0
	v_cndmask_b32_e32 v202, 0, v202, vcc
	s_add_i32 s7, s6, 11
	s_cmp_lt_u32 s7, 0x1000
	s_cselect_b64 vcc, -1, 0
	v_cndmask_b32_e32 v203, 0, v203, vcc
	s_add_i32 s7, s6, 12
	s_cmp_lt_u32 s7, 0x1000
	s_cselect_b64 vcc, -1, 0
	v_cndmask_b32_e32 v204, 0, v204, vcc
	s_add_i32 s7, s6, 13
	s_cmp_lt_u32 s7, 0x1000
	s_cselect_b64 vcc, -1, 0
	v_cndmask_b32_e32 v205, 0, v205, vcc
	s_add_i32 s7, s6, 14
	s_cmp_lt_u32 s7, 0x1000
	s_cselect_b64 vcc, -1, 0
	v_cndmask_b32_e32 v206, 0, v206, vcc
	s_add_i32 s7, s6, 15
	s_cmp_lt_u32 s7, 0x1000
	s_cselect_b64 vcc, -1, 0
	v_cndmask_b32_e32 v207, 0, v207, vcc
	s_add_i32 s7, s6, 16
	s_cmp_lt_u32 s7, 0x1000
	s_cselect_b64 vcc, -1, 0
	v_cndmask_b32_e32 v208, 0, v208, vcc
	s_add_i32 s7, s6, 17
	s_cmp_lt_u32 s7, 0x1000
	s_cselect_b64 vcc, -1, 0
	v_cndmask_b32_e32 v209, 0, v209, vcc
	s_add_i32 s7, s6, 18
	s_cmp_lt_u32 s7, 0x1000
	s_cselect_b64 vcc, -1, 0
	v_cndmask_b32_e32 v210, 0, v210, vcc
	s_add_i32 s7, s6, 19
	s_cmp_lt_u32 s7, 0x1000
	s_cselect_b64 vcc, -1, 0
	v_cndmask_b32_e32 v211, 0, v211, vcc
	s_add_i32 s7, s6, 20
	s_cmp_lt_u32 s7, 0x1000
	s_cselect_b64 vcc, -1, 0
	v_cndmask_b32_e32 v212, 0, v212, vcc
	s_add_i32 s7, s6, 21
	s_cmp_lt_u32 s7, 0x1000
	s_cselect_b64 vcc, -1, 0
	v_cndmask_b32_e32 v213, 0, v213, vcc
	s_add_i32 s7, s6, 22
	s_cmp_lt_u32 s7, 0x1000
	s_cselect_b64 vcc, -1, 0
	v_cndmask_b32_e32 v214, 0, v214, vcc
	s_add_i32 s7, s6, 23
	s_cmp_lt_u32 s7, 0x1000
	s_cselect_b64 vcc, -1, 0
	v_cndmask_b32_e32 v215, 0, v215, vcc
	s_waitcnt vmcnt(23)
	v_mul_f32_e32 v94, v94, v192
	v_mul_f32_e32 v95, v95, v192
	v_mul_f32_e32 v96, v96, v192
	v_mul_f32_e32 v97, v97, v192
	s_waitcnt vmcnt(22)
	v_mul_f32_e32 v98, v98, v193
	v_mul_f32_e32 v99, v99, v193
	v_mul_f32_e32 v100, v100, v193
	v_mul_f32_e32 v101, v101, v193
	s_waitcnt vmcnt(21)
	v_mul_f32_e32 v102, v102, v194
	v_mul_f32_e32 v103, v103, v194
	v_mul_f32_e32 v104, v104, v194
	v_mul_f32_e32 v105, v105, v194
	s_waitcnt vmcnt(20)
	v_mul_f32_e32 v106, v106, v195
	v_mul_f32_e32 v107, v107, v195
	v_mul_f32_e32 v108, v108, v195
	v_mul_f32_e32 v109, v109, v195
	s_waitcnt vmcnt(19)
	v_mul_f32_e32 v110, v110, v196
	v_mul_f32_e32 v111, v111, v196
	v_mul_f32_e32 v112, v112, v196
	v_mul_f32_e32 v113, v113, v196
	s_waitcnt vmcnt(18)
	v_mul_f32_e32 v114, v114, v197
	v_mul_f32_e32 v115, v115, v197
	v_mul_f32_e32 v116, v116, v197
	v_mul_f32_e32 v117, v117, v197
	s_waitcnt vmcnt(17)
	v_mul_f32_e32 v118, v118, v198
	v_mul_f32_e32 v119, v119, v198
	v_mul_f32_e32 v120, v120, v198
	v_mul_f32_e32 v121, v121, v198
	s_waitcnt vmcnt(16)
	v_mul_f32_e32 v122, v122, v199
	v_mul_f32_e32 v123, v123, v199
	v_mul_f32_e32 v124, v124, v199
	v_mul_f32_e32 v125, v125, v199
	s_waitcnt vmcnt(15)
	v_mul_f32_e32 v126, v126, v200
	v_mul_f32_e32 v127, v127, v200
	v_mul_f32_e32 v128, v128, v200
	v_mul_f32_e32 v129, v129, v200
	s_waitcnt vmcnt(14)
	v_mul_f32_e32 v130, v130, v201
	v_mul_f32_e32 v131, v131, v201
	v_mul_f32_e32 v132, v132, v201
	v_mul_f32_e32 v133, v133, v201
	s_waitcnt vmcnt(13)
	v_mul_f32_e32 v134, v134, v202
	v_mul_f32_e32 v135, v135, v202
	v_mul_f32_e32 v136, v136, v202
	v_mul_f32_e32 v137, v137, v202
	s_waitcnt vmcnt(12)
	v_mul_f32_e32 v138, v138, v203
	v_mul_f32_e32 v139, v139, v203
	v_mul_f32_e32 v140, v140, v203
	v_mul_f32_e32 v141, v141, v203
	s_waitcnt vmcnt(11)
	v_mul_f32_e32 v142, v142, v204
	v_mul_f32_e32 v143, v143, v204
	v_mul_f32_e32 v144, v144, v204
	v_mul_f32_e32 v145, v145, v204
	s_waitcnt vmcnt(10)
	v_mul_f32_e32 v148, v148, v205
	v_mul_f32_e32 v149, v149, v205
	v_mul_f32_e32 v150, v150, v205
	v_mul_f32_e32 v151, v151, v205
	s_waitcnt vmcnt(9)
	v_mul_f32_e32 v152, v152, v206
	v_mul_f32_e32 v153, v153, v206
	v_mul_f32_e32 v154, v154, v206
	v_mul_f32_e32 v155, v155, v206
	s_waitcnt vmcnt(8)
	v_mul_f32_e32 v156, v156, v207
	v_mul_f32_e32 v157, v157, v207
	v_mul_f32_e32 v158, v158, v207
	v_mul_f32_e32 v159, v159, v207
	s_waitcnt vmcnt(7)
	v_mul_f32_e32 v160, v160, v208
	v_mul_f32_e32 v161, v161, v208
	v_mul_f32_e32 v162, v162, v208
	v_mul_f32_e32 v163, v163, v208
	s_waitcnt vmcnt(6)
	v_mul_f32_e32 v164, v164, v209
	v_mul_f32_e32 v165, v165, v209
	v_mul_f32_e32 v166, v166, v209
	v_mul_f32_e32 v167, v167, v209
	s_waitcnt vmcnt(5)
	v_mul_f32_e32 v168, v168, v210
	v_mul_f32_e32 v169, v169, v210
	v_mul_f32_e32 v170, v170, v210
	v_mul_f32_e32 v171, v171, v210
	s_waitcnt vmcnt(4)
	v_mul_f32_e32 v172, v172, v211
	v_mul_f32_e32 v173, v173, v211
	v_mul_f32_e32 v174, v174, v211
	v_mul_f32_e32 v175, v175, v211
	s_waitcnt vmcnt(3)
	v_mul_f32_e32 v176, v176, v212
	v_mul_f32_e32 v177, v177, v212
	v_mul_f32_e32 v178, v178, v212
	v_mul_f32_e32 v179, v179, v212
	s_waitcnt vmcnt(2)
	v_mul_f32_e32 v180, v180, v213
	v_mul_f32_e32 v181, v181, v213
	v_mul_f32_e32 v182, v182, v213
	v_mul_f32_e32 v183, v183, v213
	s_waitcnt vmcnt(1)
	v_mul_f32_e32 v184, v184, v214
	v_mul_f32_e32 v185, v185, v214
	v_mul_f32_e32 v186, v186, v214
	v_mul_f32_e32 v187, v187, v214
	s_waitcnt vmcnt(0)
	v_mul_f32_e32 v188, v188, v215
	v_mul_f32_e32 v189, v189, v215
	v_mul_f32_e32 v190, v190, v215
	v_mul_f32_e32 v191, v191, v215
	s_cmp_eq_u32 s100, 1
	s_cbranch_scc1 .Lpp_h1
	s_cmp_eq_u32 s100, 2
	s_cbranch_scc1 .Lpp_h2
	s_cmp_eq_u32 s100, 4
	s_cbranch_scc1 .Lpp_h4
.Lpp_h8:
	s_cmp_lg_u32 s5, 0
	s_cbranch_scc1 .Lpp_h8_go
	v_fma_f32 v8, v4, v94, v8
	v_fma_f32 v9, v5, v95, v9
	v_fma_f32 v10, v6, v96, v10
	v_fma_f32 v11, v7, v97, v11
	v_fma_f32 v8, v4, v98, v8
	v_fma_f32 v9, v5, v99, v9
	v_fma_f32 v10, v6, v100, v10
	v_fma_f32 v11, v7, v101, v11
	v_fma_f32 v8, v4, v102, v8
	v_fma_f32 v9, v5, v103, v9
	v_fma_f32 v10, v6, v104, v10
	v_fma_f32 v11, v7, v105, v11
	v_fma_f32 v8, v4, v106, v8
	v_fma_f32 v9, v5, v107, v9
	v_fma_f32 v10, v6, v108, v10
	v_fma_f32 v11, v7, v109, v11
	v_fma_f32 v8, v4, v110, v8
	v_fma_f32 v9, v5, v111, v9
	v_fma_f32 v10, v6, v112, v10
	v_fma_f32 v11, v7, v113, v11
	v_fma_f32 v8, v4, v114, v8
	v_fma_f32 v9, v5, v115, v9
	v_fma_f32 v10, v6, v116, v10
	v_fma_f32 v11, v7, v117, v11
	v_fma_f32 v8, v4, v118, v8
	v_fma_f32 v9, v5, v119, v9
	v_fma_f32 v10, v6, v120, v10
	v_fma_f32 v11, v7, v121, v11
	v_fma_f32 v8, v4, v122, v8
	v_fma_f32 v9, v5, v123, v9
	v_fma_f32 v10, v6, v124, v10
	v_fma_f32 v11, v7, v125, v11
	v_fma_f32 v8, v4, v126, v8
	v_fma_f32 v9, v5, v127, v9
	v_fma_f32 v10, v6, v128, v10
	v_fma_f32 v11, v7, v129, v11
	v_fma_f32 v8, v4, v130, v8
	v_fma_f32 v9, v5, v131, v9
	v_fma_f32 v10, v6, v132, v10
	v_fma_f32 v11, v7, v133, v11
	v_fma_f32 v8, v4, v134, v8
	v_fma_f32 v9, v5, v135, v9
	v_fma_f32 v10, v6, v136, v10
	v_fma_f32 v11, v7, v137, v11
	v_fma_f32 v8, v4, v138, v8
	v_fma_f32 v9, v5, v139, v9
	v_fma_f32 v10, v6, v140, v10
	v_fma_f32 v11, v7, v141, v11
	v_fma_f32 v8, v4, v142, v8
	v_fma_f32 v9, v5, v143, v9
	v_fma_f32 v10, v6, v144, v10
	v_fma_f32 v11, v7, v145, v11
	v_fma_f32 v8, v4, v148, v8
	v_fma_f32 v9, v5, v149, v9
	v_fma_f32 v10, v6, v150, v10
	v_fma_f32 v11, v7, v151, v11
	v_fma_f32 v8, v4, v152, v8
	v_fma_f32 v9, v5, v153, v9
	v_fma_f32 v10, v6, v154, v10
	v_fma_f32 v11, v7, v155, v11
	v_fma_f32 v8, v4, v156, v8
	v_fma_f32 v9, v5, v157, v9
	v_fma_f32 v10, v6, v158, v10
	v_fma_f32 v11, v7, v159, v11
.Lpp_h8_go:
	s_add_i32 s7, s6, 8
	s_add_i32 s8, s7, 8
	s_min_i32 s8, s8, 0x1000
	s_sub_i32 s46, s7, 8
	s_max_i32 s46, s46, 0
	s_sub_i32 s46, s8, s46
	v_cvt_f32_i32_e32 v220, s46
	v_rcp_f32_e32 v221, v220
	v_mul_f32_e32 v216, v4, v126
	v_mul_f32_e32 v217, v5, v127
	v_mul_f32_e32 v218, v6, v128
	v_mul_f32_e32 v219, v7, v129
	v_fma_f32 v222, -v220, v221, 1.0
	v_fma_f32 v221, v222, v221, v221
	v_fma_f32 v216, v8, v221, -v216
	v_fma_f32 v217, v9, v221, -v217
	v_fma_f32 v218, v10, v221, -v218
	v_fma_f32 v219, v11, v221, -v219
	v_cvt_pk_bf16_f32 v216, v216, v217
	v_cvt_pk_bf16_f32 v217, v218, v219
	global_store_dwordx2 v[22:23], v[216:217], off
	v_fma_f32 v8, -v4, v94, v8
	v_fma_f32 v9, -v5, v95, v9
	v_fma_f32 v10, -v6, v96, v10
	v_fma_f32 v11, -v7, v97, v11
	v_fma_f32 v8, v4, v160, v8
	v_fma_f32 v9, v5, v161, v9
	v_fma_f32 v10, v6, v162, v10
	v_fma_f32 v11, v7, v163, v11
	v_lshl_add_u64 v[22:23], v[22:23], 0, s[48:49]
	s_add_i32 s7, s6, 9
	s_add_i32 s8, s7, 8
	s_min_i32 s8, s8, 0x1000
	s_sub_i32 s46, s7, 8
	s_max_i32 s46, s46, 0
	s_sub_i32 s46, s8, s46
	v_cvt_f32_i32_e32 v220, s46
	v_rcp_f32_e32 v221, v220
	v_mul_f32_e32 v216, v4, v130
	v_mul_f32_e32 v217, v5, v131
	v_mul_f32_e32 v218, v6, v132
	v_mul_f32_e32 v219, v7, v133
	v_fma_f32 v222, -v220, v221, 1.0
	v_fma_f32 v221, v222, v221, v221
	v_fma_f32 v216, v8, v221, -v216
	v_fma_f32 v217, v9, v221, -v217
	v_fma_f32 v218, v10, v221, -v218
	v_fma_f32 v219, v11, v221, -v219
	v_cvt_pk_bf16_f32 v216, v216, v217
	v_cvt_pk_bf16_f32 v217, v218, v219
	global_store_dwordx2 v[22:23], v[216:217], off
	v_fma_f32 v8, -v4, v98, v8
	v_fma_f32 v9, -v5, v99, v9
	v_fma_f32 v10, -v6, v100, v10
	v_fma_f32 v11, -v7, v101, v11
	v_fma_f32 v8, v4, v164, v8
	v_fma_f32 v9, v5, v165, v9
	v_fma_f32 v10, v6, v166, v10
	v_fma_f32 v11, v7, v167, v11
	v_lshl_add_u64 v[22:23], v[22:23], 0, s[48:49]
	s_add_i32 s7, s6, 10
	s_add_i32 s8, s7, 8
	s_min_i32 s8, s8, 0x1000
	s_sub_i32 s46, s7, 8
	s_max_i32 s46, s46, 0
	s_sub_i32 s46, s8, s46
	v_cvt_f32_i32_e32 v220, s46
	v_rcp_f32_e32 v221, v220
	v_mul_f32_e32 v216, v4, v134
	v_mul_f32_e32 v217, v5, v135
	v_mul_f32_e32 v218, v6, v136
	v_mul_f32_e32 v219, v7, v137
	v_fma_f32 v222, -v220, v221, 1.0
	v_fma_f32 v221, v222, v221, v221
	v_fma_f32 v216, v8, v221, -v216
	v_fma_f32 v217, v9, v221, -v217
	v_fma_f32 v218, v10, v221, -v218
	v_fma_f32 v219, v11, v221, -v219
	v_cvt_pk_bf16_f32 v216, v216, v217
	v_cvt_pk_bf16_f32 v217, v218, v219
	global_store_dwordx2 v[22:23], v[216:217], off
	v_fma_f32 v8, -v4, v102, v8
	v_fma_f32 v9, -v5, v103, v9
	v_fma_f32 v10, -v6, v104, v10
	v_fma_f32 v11, -v7, v105, v11
	v_fma_f32 v8, v4, v168, v8
	v_fma_f32 v9, v5, v169, v9
	v_fma_f32 v10, v6, v170, v10
	v_fma_f32 v11, v7, v171, v11
	v_lshl_add_u64 v[22:23], v[22:23], 0, s[48:49]
	s_add_i32 s7, s6, 11
	s_add_i32 s8, s7, 8
	s_min_i32 s8, s8, 0x1000
	s_sub_i32 s46, s7, 8
	s_max_i32 s46, s46, 0
	s_sub_i32 s46, s8, s46
	v_cvt_f32_i32_e32 v220, s46
	v_rcp_f32_e32 v221, v220
	v_mul_f32_e32 v216, v4, v138
	v_mul_f32_e32 v217, v5, v139
	v_mul_f32_e32 v218, v6, v140
	v_mul_f32_e32 v219, v7, v141
	v_fma_f32 v222, -v220, v221, 1.0
	v_fma_f32 v221, v222, v221, v221
	v_fma_f32 v216, v8, v221, -v216
	v_fma_f32 v217, v9, v221, -v217
	v_fma_f32 v218, v10, v221, -v218
	v_fma_f32 v219, v11, v221, -v219
	v_cvt_pk_bf16_f32 v216, v216, v217
	v_cvt_pk_bf16_f32 v217, v218, v219
	global_store_dwordx2 v[22:23], v[216:217], off
	v_fma_f32 v8, -v4, v106, v8
	v_fma_f32 v9, -v5, v107, v9
	v_fma_f32 v10, -v6, v108, v10
	v_fma_f32 v11, -v7, v109, v11
	v_fma_f32 v8, v4, v172, v8
	v_fma_f32 v9, v5, v173, v9
	v_fma_f32 v10, v6, v174, v10
	v_fma_f32 v11, v7, v175, v11
	v_lshl_add_u64 v[22:23], v[22:23], 0, s[48:49]
	s_add_i32 s7, s6, 12
	s_add_i32 s8, s7, 8
	s_min_i32 s8, s8, 0x1000
	s_sub_i32 s46, s7, 8
	s_max_i32 s46, s46, 0
	s_sub_i32 s46, s8, s46
	v_cvt_f32_i32_e32 v220, s46
	v_rcp_f32_e32 v221, v220
	v_mul_f32_e32 v216, v4, v142
	v_mul_f32_e32 v217, v5, v143
	v_mul_f32_e32 v218, v6, v144
	v_mul_f32_e32 v219, v7, v145
	v_fma_f32 v222, -v220, v221, 1.0
	v_fma_f32 v221, v222, v221, v221
	v_fma_f32 v216, v8, v221, -v216
	v_fma_f32 v217, v9, v221, -v217
	v_fma_f32 v218, v10, v221, -v218
	v_fma_f32 v219, v11, v221, -v219
	v_cvt_pk_bf16_f32 v216, v216, v217
	v_cvt_pk_bf16_f32 v217, v218, v219
	global_store_dwordx2 v[22:23], v[216:217], off
	v_fma_f32 v8, -v4, v110, v8
	v_fma_f32 v9, -v5, v111, v9
	v_fma_f32 v10, -v6, v112, v10
	v_fma_f32 v11, -v7, v113, v11
	v_fma_f32 v8, v4, v176, v8
	v_fma_f32 v9, v5, v177, v9
	v_fma_f32 v10, v6, v178, v10
	v_fma_f32 v11, v7, v179, v11
	v_lshl_add_u64 v[22:23], v[22:23], 0, s[48:49]
	s_add_i32 s7, s6, 13
	s_add_i32 s8, s7, 8
	s_min_i32 s8, s8, 0x1000
	s_sub_i32 s46, s7, 8
	s_max_i32 s46, s46, 0
	s_sub_i32 s46, s8, s46
	v_cvt_f32_i32_e32 v220, s46
	v_rcp_f32_e32 v221, v220
	v_mul_f32_e32 v216, v4, v148
	v_mul_f32_e32 v217, v5, v149
	v_mul_f32_e32 v218, v6, v150
	v_mul_f32_e32 v219, v7, v151
	v_fma_f32 v222, -v220, v221, 1.0
	v_fma_f32 v221, v222, v221, v221
	v_fma_f32 v216, v8, v221, -v216
	v_fma_f32 v217, v9, v221, -v217
	v_fma_f32 v218, v10, v221, -v218
	v_fma_f32 v219, v11, v221, -v219
	v_cvt_pk_bf16_f32 v216, v216, v217
	v_cvt_pk_bf16_f32 v217, v218, v219
	global_store_dwordx2 v[22:23], v[216:217], off
	v_fma_f32 v8, -v4, v114, v8
	v_fma_f32 v9, -v5, v115, v9
	v_fma_f32 v10, -v6, v116, v10
	v_fma_f32 v11, -v7, v117, v11
	v_fma_f32 v8, v4, v180, v8
	v_fma_f32 v9, v5, v181, v9
	v_fma_f32 v10, v6, v182, v10
	v_fma_f32 v11, v7, v183, v11
	v_lshl_add_u64 v[22:23], v[22:23], 0, s[48:49]
	s_add_i32 s7, s6, 14
	s_add_i32 s8, s7, 8
	s_min_i32 s8, s8, 0x1000
	s_sub_i32 s46, s7, 8
	s_max_i32 s46, s46, 0
	s_sub_i32 s46, s8, s46
	v_cvt_f32_i32_e32 v220, s46
	v_rcp_f32_e32 v221, v220
	v_mul_f32_e32 v216, v4, v152
	v_mul_f32_e32 v217, v5, v153
	v_mul_f32_e32 v218, v6, v154
	v_mul_f32_e32 v219, v7, v155
	v_fma_f32 v222, -v220, v221, 1.0
	v_fma_f32 v221, v222, v221, v221
	v_fma_f32 v216, v8, v221, -v216
	v_fma_f32 v217, v9, v221, -v217
	v_fma_f32 v218, v10, v221, -v218
	v_fma_f32 v219, v11, v221, -v219
	v_cvt_pk_bf16_f32 v216, v216, v217
	v_cvt_pk_bf16_f32 v217, v218, v219
	global_store_dwordx2 v[22:23], v[216:217], off
	v_fma_f32 v8, -v4, v118, v8
	v_fma_f32 v9, -v5, v119, v9
	v_fma_f32 v10, -v6, v120, v10
	v_fma_f32 v11, -v7, v121, v11
	v_fma_f32 v8, v4, v184, v8
	v_fma_f32 v9, v5, v185, v9
	v_fma_f32 v10, v6, v186, v10
	v_fma_f32 v11, v7, v187, v11
	v_lshl_add_u64 v[22:23], v[22:23], 0, s[48:49]
	s_add_i32 s7, s6, 15
	s_add_i32 s8, s7, 8
	s_min_i32 s8, s8, 0x1000
	s_sub_i32 s46, s7, 8
	s_max_i32 s46, s46, 0
	s_sub_i32 s46, s8, s46
	v_cvt_f32_i32_e32 v220, s46
	v_rcp_f32_e32 v221, v220
	v_mul_f32_e32 v216, v4, v156
	v_mul_f32_e32 v217, v5, v157
	v_mul_f32_e32 v218, v6, v158
	v_mul_f32_e32 v219, v7, v159
	v_fma_f32 v222, -v220, v221, 1.0
	v_fma_f32 v221, v222, v221, v221
	v_fma_f32 v216, v8, v221, -v216
	v_fma_f32 v217, v9, v221, -v217
	v_fma_f32 v218, v10, v221, -v218
	v_fma_f32 v219, v11, v221, -v219
	v_cvt_pk_bf16_f32 v216, v216, v217
	v_cvt_pk_bf16_f32 v217, v218, v219
	global_store_dwordx2 v[22:23], v[216:217], off
	v_fma_f32 v8, -v4, v122, v8
	v_fma_f32 v9, -v5, v123, v9
	v_fma_f32 v10, -v6, v124, v10
	v_fma_f32 v11, -v7, v125, v11
	v_fma_f32 v8, v4, v188, v8
	v_fma_f32 v9, v5, v189, v9
	v_fma_f32 v10, v6, v190, v10
	v_fma_f32 v11, v7, v191, v11
	v_lshl_add_u64 v[22:23], v[22:23], 0, s[48:49]
	s_branch .Lpp_next
.Lpp_h4:
	s_cmp_lg_u32 s5, 0
	s_cbranch_scc1 .Lpp_h4_go
	v_fma_f32 v8, v4, v110, v8
	v_fma_f32 v9, v5, v111, v9
	v_fma_f32 v10, v6, v112, v10
	v_fma_f32 v11, v7, v113, v11
	v_fma_f32 v8, v4, v114, v8
	v_fma_f32 v9, v5, v115, v9
	v_fma_f32 v10, v6, v116, v10
	v_fma_f32 v11, v7, v117, v11
	v_fma_f32 v8, v4, v118, v8
	v_fma_f32 v9, v5, v119, v9
	v_fma_f32 v10, v6, v120, v10
	v_fma_f32 v11, v7, v121, v11
	v_fma_f32 v8, v4, v122, v8
	v_fma_f32 v9, v5, v123, v9
	v_fma_f32 v10, v6, v124, v10
	v_fma_f32 v11, v7, v125, v11
	v_fma_f32 v8, v4, v126, v8
	v_fma_f32 v9, v5, v127, v9
	v_fma_f32 v10, v6, v128, v10
	v_fma_f32 v11, v7, v129, v11
	v_fma_f32 v8, v4, v130, v8
	v_fma_f32 v9, v5, v131, v9
	v_fma_f32 v10, v6, v132, v10
	v_fma_f32 v11, v7, v133, v11
	v_fma_f32 v8, v4, v134, v8
	v_fma_f32 v9, v5, v135, v9
	v_fma_f32 v10, v6, v136, v10
	v_fma_f32 v11, v7, v137, v11
	v_fma_f32 v8, v4, v138, v8
	v_fma_f32 v9, v5, v139, v9
	v_fma_f32 v10, v6, v140, v10
	v_fma_f32 v11, v7, v141, v11
.Lpp_h4_go:
	s_add_i32 s7, s6, 8
	s_add_i32 s8, s7, 4
	s_min_i32 s8, s8, 0x1000
	s_sub_i32 s46, s7, 4
	s_max_i32 s46, s46, 0
	s_sub_i32 s46, s8, s46
	v_cvt_f32_i32_e32 v220, s46
	v_rcp_f32_e32 v221, v220
	v_mul_f32_e32 v216, v4, v126
	v_mul_f32_e32 v217, v5, v127
	v_mul_f32_e32 v218, v6, v128
	v_mul_f32_e32 v219, v7, v129
	v_fma_f32 v222, -v220, v221, 1.0
	v_fma_f32 v221, v222, v221, v221
	v_fma_f32 v216, v8, v221, -v216
	v_fma_f32 v217, v9, v221, -v217
	v_fma_f32 v218, v10, v221, -v218
	v_fma_f32 v219, v11, v221, -v219
	v_cvt_pk_bf16_f32 v216, v216, v217
	v_cvt_pk_bf16_f32 v217, v218, v219
	global_store_dwordx2 v[22:23], v[216:217], off
	v_fma_f32 v8, -v4, v110, v8
	v_fma_f32 v9, -v5, v111, v9
	v_fma_f32 v10, -v6, v112, v10
	v_fma_f32 v11, -v7, v113, v11
	v_fma_f32 v8, v4, v142, v8
	v_fma_f32 v9, v5, v143, v9
	v_fma_f32 v10, v6, v144, v10
	v_fma_f32 v11, v7, v145, v11
	v_lshl_add_u64 v[22:23], v[22:23], 0, s[48:49]
	s_add_i32 s7, s6, 9
	s_add_i32 s8, s7, 4
	s_min_i32 s8, s8, 0x1000
	s_sub_i32 s46, s7, 4
	s_max_i32 s46, s46, 0
	s_sub_i32 s46, s8, s46
	v_cvt_f32_i32_e32 v220, s46
	v_rcp_f32_e32 v221, v220
	v_mul_f32_e32 v216, v4, v130
	v_mul_f32_e32 v217, v5, v131
	v_mul_f32_e32 v218, v6, v132
	v_mul_f32_e32 v219, v7, v133
	v_fma_f32 v222, -v220, v221, 1.0
	v_fma_f32 v221, v222, v221, v221
	v_fma_f32 v216, v8, v221, -v216
	v_fma_f32 v217, v9, v221, -v217
	v_fma_f32 v218, v10, v221, -v218
	v_fma_f32 v219, v11, v221, -v219
	v_cvt_pk_bf16_f32 v216, v216, v217
	v_cvt_pk_bf16_f32 v217, v218, v219
	global_store_dwordx2 v[22:23], v[216:217], off
	v_fma_f32 v8, -v4, v114, v8
	v_fma_f32 v9, -v5, v115, v9
	v_fma_f32 v10, -v6, v116, v10
	v_fma_f32 v11, -v7, v117, v11
	v_fma_f32 v8, v4, v148, v8
	v_fma_f32 v9, v5, v149, v9
	v_fma_f32 v10, v6, v150, v10
	v_fma_f32 v11, v7, v151, v11
	v_lshl_add_u64 v[22:23], v[22:23], 0, s[48:49]
	s_add_i32 s7, s6, 10
	s_add_i32 s8, s7, 4
	s_min_i32 s8, s8, 0x1000
	s_sub_i32 s46, s7, 4
	s_max_i32 s46, s46, 0
	s_sub_i32 s46, s8, s46
	v_cvt_f32_i32_e32 v220, s46
	v_rcp_f32_e32 v221, v220
	v_mul_f32_e32 v216, v4, v134
	v_mul_f32_e32 v217, v5, v135
	v_mul_f32_e32 v218, v6, v136
	v_mul_f32_e32 v219, v7, v137
	v_fma_f32 v222, -v220, v221, 1.0
	v_fma_f32 v221, v222, v221, v221
	v_fma_f32 v216, v8, v221, -v216
	v_fma_f32 v217, v9, v221, -v217
	v_fma_f32 v218, v10, v221, -v218
	v_fma_f32 v219, v11, v221, -v219
	v_cvt_pk_bf16_f32 v216, v216, v217
	v_cvt_pk_bf16_f32 v217, v218, v219
	global_store_dwordx2 v[22:23], v[216:217], off
	v_fma_f32 v8, -v4, v118, v8
	v_fma_f32 v9, -v5, v119, v9
	v_fma_f32 v10, -v6, v120, v10
	v_fma_f32 v11, -v7, v121, v11
	v_fma_f32 v8, v4, v152, v8
	v_fma_f32 v9, v5, v153, v9
	v_fma_f32 v10, v6, v154, v10
	v_fma_f32 v11, v7, v155, v11
	v_lshl_add_u64 v[22:23], v[22:23], 0, s[48:49]
	s_add_i32 s7, s6, 11
	s_add_i32 s8, s7, 4
	s_min_i32 s8, s8, 0x1000
	s_sub_i32 s46, s7, 4
	s_max_i32 s46, s46, 0
	s_sub_i32 s46, s8, s46
	v_cvt_f32_i32_e32 v220, s46
	v_rcp_f32_e32 v221, v220
	v_mul_f32_e32 v216, v4, v138
	v_mul_f32_e32 v217, v5, v139
	v_mul_f32_e32 v218, v6, v140
	v_mul_f32_e32 v219, v7, v141
	v_fma_f32 v222, -v220, v221, 1.0
	v_fma_f32 v221, v222, v221, v221
	v_fma_f32 v216, v8, v221, -v216
	v_fma_f32 v217, v9, v221, -v217
	v_fma_f32 v218, v10, v221, -v218
	v_fma_f32 v219, v11, v221, -v219
	v_cvt_pk_bf16_f32 v216, v216, v217
	v_cvt_pk_bf16_f32 v217, v218, v219
	global_store_dwordx2 v[22:23], v[216:217], off
	v_fma_f32 v8, -v4, v122, v8
	v_fma_f32 v9, -v5, v123, v9
	v_fma_f32 v10, -v6, v124, v10
	v_fma_f32 v11, -v7, v125, v11
	v_fma_f32 v8, v4, v156, v8
	v_fma_f32 v9, v5, v157, v9
	v_fma_f32 v10, v6, v158, v10
	v_fma_f32 v11, v7, v159, v11
	v_lshl_add_u64 v[22:23], v[22:23], 0, s[48:49]
	s_add_i32 s7, s6, 12
	s_add_i32 s8, s7, 4
	s_min_i32 s8, s8, 0x1000
	s_sub_i32 s46, s7, 4
	s_max_i32 s46, s46, 0
	s_sub_i32 s46, s8, s46
	v_cvt_f32_i32_e32 v220, s46
	v_rcp_f32_e32 v221, v220
	v_mul_f32_e32 v216, v4, v142
	v_mul_f32_e32 v217, v5, v143
	v_mul_f32_e32 v218, v6, v144
	v_mul_f32_e32 v219, v7, v145
	v_fma_f32 v222, -v220, v221, 1.0
	v_fma_f32 v221, v222, v221, v221
	v_fma_f32 v216, v8, v221, -v216
	v_fma_f32 v217, v9, v221, -v217
	v_fma_f32 v218, v10, v221, -v218
	v_fma_f32 v219, v11, v221, -v219
	v_cvt_pk_bf16_f32 v216, v216, v217
	v_cvt_pk_bf16_f32 v217, v218, v219
	global_store_dwordx2 v[22:23], v[216:217], off
	v_fma_f32 v8, -v4, v126, v8
	v_fma_f32 v9, -v5, v127, v9
	v_fma_f32 v10, -v6, v128, v10
	v_fma_f32 v11, -v7, v129, v11
	v_fma_f32 v8, v4, v160, v8
	v_fma_f32 v9, v5, v161, v9
	v_fma_f32 v10, v6, v162, v10
	v_fma_f32 v11, v7, v163, v11
	v_lshl_add_u64 v[22:23], v[22:23], 0, s[48:49]
	s_add_i32 s7, s6, 13
	s_add_i32 s8, s7, 4
	s_min_i32 s8, s8, 0x1000
	s_sub_i32 s46, s7, 4
	s_max_i32 s46, s46, 0
	s_sub_i32 s46, s8, s46
	v_cvt_f32_i32_e32 v220, s46
	v_rcp_f32_e32 v221, v220
	v_mul_f32_e32 v216, v4, v148
	v_mul_f32_e32 v217, v5, v149
	v_mul_f32_e32 v218, v6, v150
	v_mul_f32_e32 v219, v7, v151
	v_fma_f32 v222, -v220, v221, 1.0
	v_fma_f32 v221, v222, v221, v221
	v_fma_f32 v216, v8, v221, -v216
	v_fma_f32 v217, v9, v221, -v217
	v_fma_f32 v218, v10, v221, -v218
	v_fma_f32 v219, v11, v221, -v219
	v_cvt_pk_bf16_f32 v216, v216, v217
	v_cvt_pk_bf16_f32 v217, v218, v219
	global_store_dwordx2 v[22:23], v[216:217], off
	v_fma_f32 v8, -v4, v130, v8
	v_fma_f32 v9, -v5, v131, v9
	v_fma_f32 v10, -v6, v132, v10
	v_fma_f32 v11, -v7, v133, v11
	v_fma_f32 v8, v4, v164, v8
	v_fma_f32 v9, v5, v165, v9
	v_fma_f32 v10, v6, v166, v10
	v_fma_f32 v11, v7, v167, v11
	v_lshl_add_u64 v[22:23], v[22:23], 0, s[48:49]
	s_add_i32 s7, s6, 14
	s_add_i32 s8, s7, 4
	s_min_i32 s8, s8, 0x1000
	s_sub_i32 s46, s7, 4
	s_max_i32 s46, s46, 0
	s_sub_i32 s46, s8, s46
	v_cvt_f32_i32_e32 v220, s46
	v_rcp_f32_e32 v221, v220
	v_mul_f32_e32 v216, v4, v152
	v_mul_f32_e32 v217, v5, v153
	v_mul_f32_e32 v218, v6, v154
	v_mul_f32_e32 v219, v7, v155
	v_fma_f32 v222, -v220, v221, 1.0
	v_fma_f32 v221, v222, v221, v221
	v_fma_f32 v216, v8, v221, -v216
	v_fma_f32 v217, v9, v221, -v217
	v_fma_f32 v218, v10, v221, -v218
	v_fma_f32 v219, v11, v221, -v219
	v_cvt_pk_bf16_f32 v216, v216, v217
	v_cvt_pk_bf16_f32 v217, v218, v219
	global_store_dwordx2 v[22:23], v[216:217], off
	v_fma_f32 v8, -v4, v134, v8
	v_fma_f32 v9, -v5, v135, v9
	v_fma_f32 v10, -v6, v136, v10
	v_fma_f32 v11, -v7, v137, v11
	v_fma_f32 v8, v4, v168, v8
	v_fma_f32 v9, v5, v169, v9
	v_fma_f32 v10, v6, v170, v10
	v_fma_f32 v11, v7, v171, v11
	v_lshl_add_u64 v[22:23], v[22:23], 0, s[48:49]
	s_add_i32 s7, s6, 15
	s_add_i32 s8, s7, 4
	s_min_i32 s8, s8, 0x1000
	s_sub_i32 s46, s7, 4
	s_max_i32 s46, s46, 0
	s_sub_i32 s46, s8, s46
	v_cvt_f32_i32_e32 v220, s46
	v_rcp_f32_e32 v221, v220
	v_mul_f32_e32 v216, v4, v156
	v_mul_f32_e32 v217, v5, v157
	v_mul_f32_e32 v218, v6, v158
	v_mul_f32_e32 v219, v7, v159
	v_fma_f32 v222, -v220, v221, 1.0
	v_fma_f32 v221, v222, v221, v221
	v_fma_f32 v216, v8, v221, -v216
	v_fma_f32 v217, v9, v221, -v217
	v_fma_f32 v218, v10, v221, -v218
	v_fma_f32 v219, v11, v221, -v219
	v_cvt_pk_bf16_f32 v216, v216, v217
	v_cvt_pk_bf16_f32 v217, v218, v219
	global_store_dwordx2 v[22:23], v[216:217], off
	v_fma_f32 v8, -v4, v138, v8
	v_fma_f32 v9, -v5, v139, v9
	v_fma_f32 v10, -v6, v140, v10
	v_fma_f32 v11, -v7, v141, v11
	v_fma_f32 v8, v4, v172, v8
	v_fma_f32 v9, v5, v173, v9
	v_fma_f32 v10, v6, v174, v10
	v_fma_f32 v11, v7, v175, v11
	v_lshl_add_u64 v[22:23], v[22:23], 0, s[48:49]
	s_branch .Lpp_next
.Lpp_h2:
	s_cmp_lg_u32 s5, 0
	s_cbranch_scc1 .Lpp_h2_go
	v_fma_f32 v8, v4, v118, v8
	v_fma_f32 v9, v5, v119, v9
	v_fma_f32 v10, v6, v120, v10
	v_fma_f32 v11, v7, v121, v11
	v_fma_f32 v8, v4, v122, v8
	v_fma_f32 v9, v5, v123, v9
	v_fma_f32 v10, v6, v124, v10
	v_fma_f32 v11, v7, v125, v11
	v_fma_f32 v8, v4, v126, v8
	v_fma_f32 v9, v5, v127, v9
	v_fma_f32 v10, v6, v128, v10
	v_fma_f32 v11, v7, v129, v11
	v_fma_f32 v8, v4, v130, v8
	v_fma_f32 v9, v5, v131, v9
	v_fma_f32 v10, v6, v132, v10
	v_fma_f32 v11, v7, v133, v11
.Lpp_h2_go:
	s_add_i32 s7, s6, 8
	s_add_i32 s8, s7, 2
	s_min_i32 s8, s8, 0x1000
	s_sub_i32 s46, s7, 2
	s_max_i32 s46, s46, 0
	s_sub_i32 s46, s8, s46
	v_cvt_f32_i32_e32 v220, s46
	v_rcp_f32_e32 v221, v220
	v_mul_f32_e32 v216, v4, v126
	v_mul_f32_e32 v217, v5, v127
	v_mul_f32_e32 v218, v6, v128
	v_mul_f32_e32 v219, v7, v129
	v_fma_f32 v222, -v220, v221, 1.0
	v_fma_f32 v221, v222, v221, v221
	v_fma_f32 v216, v8, v221, -v216
	v_fma_f32 v217, v9, v221, -v217
	v_fma_f32 v218, v10, v221, -v218
	v_fma_f32 v219, v11, v221, -v219
	v_cvt_pk_bf16_f32 v216, v216, v217
	v_cvt_pk_bf16_f32 v217, v218, v219
	global_store_dwordx2 v[22:23], v[216:217], off
	v_fma_f32 v8, -v4, v118, v8
	v_fma_f32 v9, -v5, v119, v9
	v_fma_f32 v10, -v6, v120, v10
	v_fma_f32 v11, -v7, v121, v11
	v_fma_f32 v8, v4, v134, v8
	v_fma_f32 v9, v5, v135, v9
	v_fma_f32 v10, v6, v136, v10
	v_fma_f32 v11, v7, v137, v11
	v_lshl_add_u64 v[22:23], v[22:23], 0, s[48:49]
	s_add_i32 s7, s6, 9
	s_add_i32 s8, s7, 2
	s_min_i32 s8, s8, 0x1000
	s_sub_i32 s46, s7, 2
	s_max_i32 s46, s46, 0
	s_sub_i32 s46, s8, s46
	v_cvt_f32_i32_e32 v220, s46
	v_rcp_f32_e32 v221, v220
	v_mul_f32_e32 v216, v4, v130
	v_mul_f32_e32 v217, v5, v131
	v_mul_f32_e32 v218, v6, v132
	v_mul_f32_e32 v219, v7, v133
	v_fma_f32 v222, -v220, v221, 1.0
	v_fma_f32 v221, v222, v221, v221
	v_fma_f32 v216, v8, v221, -v216
	v_fma_f32 v217, v9, v221, -v217
	v_fma_f32 v218, v10, v221, -v218
	v_fma_f32 v219, v11, v221, -v219
	v_cvt_pk_bf16_f32 v216, v216, v217
	v_cvt_pk_bf16_f32 v217, v218, v219
	global_store_dwordx2 v[22:23], v[216:217], off
	v_fma_f32 v8, -v4, v122, v8
	v_fma_f32 v9, -v5, v123, v9
	v_fma_f32 v10, -v6, v124, v10
	v_fma_f32 v11, -v7, v125, v11
	v_fma_f32 v8, v4, v138, v8
	v_fma_f32 v9, v5, v139, v9
	v_fma_f32 v10, v6, v140, v10
	v_fma_f32 v11, v7, v141, v11
	v_lshl_add_u64 v[22:23], v[22:23], 0, s[48:49]
	s_add_i32 s7, s6, 10
	s_add_i32 s8, s7, 2
	s_min_i32 s8, s8, 0x1000
	s_sub_i32 s46, s7, 2
	s_max_i32 s46, s46, 0
	s_sub_i32 s46, s8, s46
	v_cvt_f32_i32_e32 v220, s46
	v_rcp_f32_e32 v221, v220
	v_mul_f32_e32 v216, v4, v134
	v_mul_f32_e32 v217, v5, v135
	v_mul_f32_e32 v218, v6, v136
	v_mul_f32_e32 v219, v7, v137
	v_fma_f32 v222, -v220, v221, 1.0
	v_fma_f32 v221, v222, v221, v221
	v_fma_f32 v216, v8, v221, -v216
	v_fma_f32 v217, v9, v221, -v217
	v_fma_f32 v218, v10, v221, -v218
	v_fma_f32 v219, v11, v221, -v219
	v_cvt_pk_bf16_f32 v216, v216, v217
	v_cvt_pk_bf16_f32 v217, v218, v219
	global_store_dwordx2 v[22:23], v[216:217], off
	v_fma_f32 v8, -v4, v126, v8
	v_fma_f32 v9, -v5, v127, v9
	v_fma_f32 v10, -v6, v128, v10
	v_fma_f32 v11, -v7, v129, v11
	v_fma_f32 v8, v4, v142, v8
	v_fma_f32 v9, v5, v143, v9
	v_fma_f32 v10, v6, v144, v10
	v_fma_f32 v11, v7, v145, v11
	v_lshl_add_u64 v[22:23], v[22:23], 0, s[48:49]
	s_add_i32 s7, s6, 11
	s_add_i32 s8, s7, 2
	s_min_i32 s8, s8, 0x1000
	s_sub_i32 s46, s7, 2
	s_max_i32 s46, s46, 0
	s_sub_i32 s46, s8, s46
	v_cvt_f32_i32_e32 v220, s46
	v_rcp_f32_e32 v221, v220
	v_mul_f32_e32 v216, v4, v138
	v_mul_f32_e32 v217, v5, v139
	v_mul_f32_e32 v218, v6, v140
	v_mul_f32_e32 v219, v7, v141
	v_fma_f32 v222, -v220, v221, 1.0
	v_fma_f32 v221, v222, v221, v221
	v_fma_f32 v216, v8, v221, -v216
	v_fma_f32 v217, v9, v221, -v217
	v_fma_f32 v218, v10, v221, -v218
	v_fma_f32 v219, v11, v221, -v219
	v_cvt_pk_bf16_f32 v216, v216, v217
	v_cvt_pk_bf16_f32 v217, v218, v219
	global_store_dwordx2 v[22:23], v[216:217], off
	v_fma_f32 v8, -v4, v130, v8
	v_fma_f32 v9, -v5, v131, v9
	v_fma_f32 v10, -v6, v132, v10
	v_fma_f32 v11, -v7, v133, v11
	v_fma_f32 v8, v4, v148, v8
	v_fma_f32 v9, v5, v149, v9
	v_fma_f32 v10, v6, v150, v10
	v_fma_f32 v11, v7, v151, v11
	v_lshl_add_u64 v[22:23], v[22:23], 0, s[48:49]
	s_add_i32 s7, s6, 12
	s_add_i32 s8, s7, 2
	s_min_i32 s8, s8, 0x1000
	s_sub_i32 s46, s7, 2
	s_max_i32 s46, s46, 0
	s_sub_i32 s46, s8, s46
	v_cvt_f32_i32_e32 v220, s46
	v_rcp_f32_e32 v221, v220
	v_mul_f32_e32 v216, v4, v142
	v_mul_f32_e32 v217, v5, v143
	v_mul_f32_e32 v218, v6, v144
	v_mul_f32_e32 v219, v7, v145
	v_fma_f32 v222, -v220, v221, 1.0
	v_fma_f32 v221, v222, v221, v221
	v_fma_f32 v216, v8, v221, -v216
	v_fma_f32 v217, v9, v221, -v217
	v_fma_f32 v218, v10, v221, -v218
	v_fma_f32 v219, v11, v221, -v219
	v_cvt_pk_bf16_f32 v216, v216, v217
	v_cvt_pk_bf16_f32 v217, v218, v219
	global_store_dwordx2 v[22:23], v[216:217], off
	v_fma_f32 v8, -v4, v134, v8
	v_fma_f32 v9, -v5, v135, v9
	v_fma_f32 v10, -v6, v136, v10
	v_fma_f32 v11, -v7, v137, v11
	v_fma_f32 v8, v4, v152, v8
	v_fma_f32 v9, v5, v153, v9
	v_fma_f32 v10, v6, v154, v10
	v_fma_f32 v11, v7, v155, v11
	v_lshl_add_u64 v[22:23], v[22:23], 0, s[48:49]
	s_add_i32 s7, s6, 13
	s_add_i32 s8, s7, 2
	s_min_i32 s8, s8, 0x1000
	s_sub_i32 s46, s7, 2
	s_max_i32 s46, s46, 0
	s_sub_i32 s46, s8, s46
	v_cvt_f32_i32_e32 v220, s46
	v_rcp_f32_e32 v221, v220
	v_mul_f32_e32 v216, v4, v148
	v_mul_f32_e32 v217, v5, v149
	v_mul_f32_e32 v218, v6, v150
	v_mul_f32_e32 v219, v7, v151
	v_fma_f32 v222, -v220, v221, 1.0
	v_fma_f32 v221, v222, v221, v221
	v_fma_f32 v216, v8, v221, -v216
	v_fma_f32 v217, v9, v221, -v217
	v_fma_f32 v218, v10, v221, -v218
	v_fma_f32 v219, v11, v221, -v219
	v_cvt_pk_bf16_f32 v216, v216, v217
	v_cvt_pk_bf16_f32 v217, v218, v219
	global_store_dwordx2 v[22:23], v[216:217], off
	v_fma_f32 v8, -v4, v138, v8
	v_fma_f32 v9, -v5, v139, v9
	v_fma_f32 v10, -v6, v140, v10
	v_fma_f32 v11, -v7, v141, v11
	v_fma_f32 v8, v4, v156, v8
	v_fma_f32 v9, v5, v157, v9
	v_fma_f32 v10, v6, v158, v10
	v_fma_f32 v11, v7, v159, v11
	v_lshl_add_u64 v[22:23], v[22:23], 0, s[48:49]
	s_add_i32 s7, s6, 14
	s_add_i32 s8, s7, 2
	s_min_i32 s8, s8, 0x1000
	s_sub_i32 s46, s7, 2
	s_max_i32 s46, s46, 0
	s_sub_i32 s46, s8, s46
	v_cvt_f32_i32_e32 v220, s46
	v_rcp_f32_e32 v221, v220
	v_mul_f32_e32 v216, v4, v152
	v_mul_f32_e32 v217, v5, v153
	v_mul_f32_e32 v218, v6, v154
	v_mul_f32_e32 v219, v7, v155
	v_fma_f32 v222, -v220, v221, 1.0
	v_fma_f32 v221, v222, v221, v221
	v_fma_f32 v216, v8, v221, -v216
	v_fma_f32 v217, v9, v221, -v217
	v_fma_f32 v218, v10, v221, -v218
	v_fma_f32 v219, v11, v221, -v219
	v_cvt_pk_bf16_f32 v216, v216, v217
	v_cvt_pk_bf16_f32 v217, v218, v219
	global_store_dwordx2 v[22:23], v[216:217], off
	v_fma_f32 v8, -v4, v142, v8
	v_fma_f32 v9, -v5, v143, v9
	v_fma_f32 v10, -v6, v144, v10
	v_fma_f32 v11, -v7, v145, v11
	v_fma_f32 v8, v4, v160, v8
	v_fma_f32 v9, v5, v161, v9
	v_fma_f32 v10, v6, v162, v10
	v_fma_f32 v11, v7, v163, v11
	v_lshl_add_u64 v[22:23], v[22:23], 0, s[48:49]
	s_add_i32 s7, s6, 15
	s_add_i32 s8, s7, 2
	s_min_i32 s8, s8, 0x1000
	s_sub_i32 s46, s7, 2
	s_max_i32 s46, s46, 0
	s_sub_i32 s46, s8, s46
	v_cvt_f32_i32_e32 v220, s46
	v_rcp_f32_e32 v221, v220
	v_mul_f32_e32 v216, v4, v156
	v_mul_f32_e32 v217, v5, v157
	v_mul_f32_e32 v218, v6, v158
	v_mul_f32_e32 v219, v7, v159
	v_fma_f32 v222, -v220, v221, 1.0
	v_fma_f32 v221, v222, v221, v221
	v_fma_f32 v216, v8, v221, -v216
	v_fma_f32 v217, v9, v221, -v217
	v_fma_f32 v218, v10, v221, -v218
	v_fma_f32 v219, v11, v221, -v219
	v_cvt_pk_bf16_f32 v216, v216, v217
	v_cvt_pk_bf16_f32 v217, v218, v219
	global_store_dwordx2 v[22:23], v[216:217], off
	v_fma_f32 v8, -v4, v148, v8
	v_fma_f32 v9, -v5, v149, v9
	v_fma_f32 v10, -v6, v150, v10
	v_fma_f32 v11, -v7, v151, v11
	v_fma_f32 v8, v4, v164, v8
	v_fma_f32 v9, v5, v165, v9
	v_fma_f32 v10, v6, v166, v10
	v_fma_f32 v11, v7, v167, v11
	v_lshl_add_u64 v[22:23], v[22:23], 0, s[48:49]
	s_branch .Lpp_next
.Lpp_h1:
	s_cmp_lg_u32 s5, 0
	s_cbranch_scc1 .Lpp_h1_go
	v_fma_f32 v8, v4, v122, v8
	v_fma_f32 v9, v5, v123, v9
	v_fma_f32 v10, v6, v124, v10
	v_fma_f32 v11, v7, v125, v11
	v_fma_f32 v8, v4, v126, v8
	v_fma_f32 v9, v5, v127, v9
	v_fma_f32 v10, v6, v128, v10
	v_fma_f32 v11, v7, v129, v11
.Lpp_h1_go:
	s_add_i32 s7, s6, 8
	s_add_i32 s8, s7, 1
	s_min_i32 s8, s8, 0x1000
	s_sub_i32 s46, s7, 1
	s_max_i32 s46, s46, 0
	s_sub_i32 s46, s8, s46
	v_cvt_f32_i32_e32 v220, s46
	v_rcp_f32_e32 v221, v220
	v_mul_f32_e32 v216, v4, v126
	v_mul_f32_e32 v217, v5, v127
	v_mul_f32_e32 v218, v6, v128
	v_mul_f32_e32 v219, v7, v129
	v_fma_f32 v222, -v220, v221, 1.0
	v_fma_f32 v221, v222, v221, v221
	v_fma_f32 v216, v8, v221, -v216
	v_fma_f32 v217, v9, v221, -v217
	v_fma_f32 v218, v10, v221, -v218
	v_fma_f32 v219, v11, v221, -v219
	v_cvt_pk_bf16_f32 v216, v216, v217
	v_cvt_pk_bf16_f32 v217, v218, v219
	global_store_dwordx2 v[22:23], v[216:217], off
	v_fma_f32 v8, -v4, v122, v8
	v_fma_f32 v9, -v5, v123, v9
	v_fma_f32 v10, -v6, v124, v10
	v_fma_f32 v11, -v7, v125, v11
	v_fma_f32 v8, v4, v130, v8
	v_fma_f32 v9, v5, v131, v9
	v_fma_f32 v10, v6, v132, v10
	v_fma_f32 v11, v7, v133, v11
	v_lshl_add_u64 v[22:23], v[22:23], 0, s[48:49]
	s_add_i32 s7, s6, 9
	s_add_i32 s8, s7, 1
	s_min_i32 s8, s8, 0x1000
	s_sub_i32 s46, s7, 1
	s_max_i32 s46, s46, 0
	s_sub_i32 s46, s8, s46
	v_cvt_f32_i32_e32 v220, s46
	v_rcp_f32_e32 v221, v220
	v_mul_f32_e32 v216, v4, v130
	v_mul_f32_e32 v217, v5, v131
	v_mul_f32_e32 v218, v6, v132
	v_mul_f32_e32 v219, v7, v133
	v_fma_f32 v222, -v220, v221, 1.0
	v_fma_f32 v221, v222, v221, v221
	v_fma_f32 v216, v8, v221, -v216
	v_fma_f32 v217, v9, v221, -v217
	v_fma_f32 v218, v10, v221, -v218
	v_fma_f32 v219, v11, v221, -v219
	v_cvt_pk_bf16_f32 v216, v216, v217
	v_cvt_pk_bf16_f32 v217, v218, v219
	global_store_dwordx2 v[22:23], v[216:217], off
	v_fma_f32 v8, -v4, v126, v8
	v_fma_f32 v9, -v5, v127, v9
	v_fma_f32 v10, -v6, v128, v10
	v_fma_f32 v11, -v7, v129, v11
	v_fma_f32 v8, v4, v134, v8
	v_fma_f32 v9, v5, v135, v9
	v_fma_f32 v10, v6, v136, v10
	v_fma_f32 v11, v7, v137, v11
	v_lshl_add_u64 v[22:23], v[22:23], 0, s[48:49]
	s_add_i32 s7, s6, 10
	s_add_i32 s8, s7, 1
	s_min_i32 s8, s8, 0x1000
	s_sub_i32 s46, s7, 1
	s_max_i32 s46, s46, 0
	s_sub_i32 s46, s8, s46
	v_cvt_f32_i32_e32 v220, s46
	v_rcp_f32_e32 v221, v220
	v_mul_f32_e32 v216, v4, v134
	v_mul_f32_e32 v217, v5, v135
	v_mul_f32_e32 v218, v6, v136
	v_mul_f32_e32 v219, v7, v137
	v_fma_f32 v222, -v220, v221, 1.0
	v_fma_f32 v221, v222, v221, v221
	v_fma_f32 v216, v8, v221, -v216
	v_fma_f32 v217, v9, v221, -v217
	v_fma_f32 v218, v10, v221, -v218
	v_fma_f32 v219, v11, v221, -v219
	v_cvt_pk_bf16_f32 v216, v216, v217
	v_cvt_pk_bf16_f32 v217, v218, v219
	global_store_dwordx2 v[22:23], v[216:217], off
	v_fma_f32 v8, -v4, v130, v8
	v_fma_f32 v9, -v5, v131, v9
	v_fma_f32 v10, -v6, v132, v10
	v_fma_f32 v11, -v7, v133, v11
	v_fma_f32 v8, v4, v138, v8
	v_fma_f32 v9, v5, v139, v9
	v_fma_f32 v10, v6, v140, v10
	v_fma_f32 v11, v7, v141, v11
	v_lshl_add_u64 v[22:23], v[22:23], 0, s[48:49]
	s_add_i32 s7, s6, 11
	s_add_i32 s8, s7, 1
	s_min_i32 s8, s8, 0x1000
	s_sub_i32 s46, s7, 1
	s_max_i32 s46, s46, 0
	s_sub_i32 s46, s8, s46
	v_cvt_f32_i32_e32 v220, s46
	v_rcp_f32_e32 v221, v220
	v_mul_f32_e32 v216, v4, v138
	v_mul_f32_e32 v217, v5, v139
	v_mul_f32_e32 v218, v6, v140
	v_mul_f32_e32 v219, v7, v141
	v_fma_f32 v222, -v220, v221, 1.0
	v_fma_f32 v221, v222, v221, v221
	v_fma_f32 v216, v8, v221, -v216
	v_fma_f32 v217, v9, v221, -v217
	v_fma_f32 v218, v10, v221, -v218
	v_fma_f32 v219, v11, v221, -v219
	v_cvt_pk_bf16_f32 v216, v216, v217
	v_cvt_pk_bf16_f32 v217, v218, v219
	global_store_dwordx2 v[22:23], v[216:217], off
	v_fma_f32 v8, -v4, v134, v8
	v_fma_f32 v9, -v5, v135, v9
	v_fma_f32 v10, -v6, v136, v10
	v_fma_f32 v11, -v7, v137, v11
	v_fma_f32 v8, v4, v142, v8
	v_fma_f32 v9, v5, v143, v9
	v_fma_f32 v10, v6, v144, v10
	v_fma_f32 v11, v7, v145, v11
	v_lshl_add_u64 v[22:23], v[22:23], 0, s[48:49]
	s_add_i32 s7, s6, 12
	s_add_i32 s8, s7, 1
	s_min_i32 s8, s8, 0x1000
	s_sub_i32 s46, s7, 1
	s_max_i32 s46, s46, 0
	s_sub_i32 s46, s8, s46
	v_cvt_f32_i32_e32 v220, s46
	v_rcp_f32_e32 v221, v220
	v_mul_f32_e32 v216, v4, v142
	v_mul_f32_e32 v217, v5, v143
	v_mul_f32_e32 v218, v6, v144
	v_mul_f32_e32 v219, v7, v145
	v_fma_f32 v222, -v220, v221, 1.0
	v_fma_f32 v221, v222, v221, v221
	v_fma_f32 v216, v8, v221, -v216
	v_fma_f32 v217, v9, v221, -v217
	v_fma_f32 v218, v10, v221, -v218
	v_fma_f32 v219, v11, v221, -v219
	v_cvt_pk_bf16_f32 v216, v216, v217
	v_cvt_pk_bf16_f32 v217, v218, v219
	global_store_dwordx2 v[22:23], v[216:217], off
	v_fma_f32 v8, -v4, v138, v8
	v_fma_f32 v9, -v5, v139, v9
	v_fma_f32 v10, -v6, v140, v10
	v_fma_f32 v11, -v7, v141, v11
	v_fma_f32 v8, v4, v148, v8
	v_fma_f32 v9, v5, v149, v9
	v_fma_f32 v10, v6, v150, v10
	v_fma_f32 v11, v7, v151, v11
	v_lshl_add_u64 v[22:23], v[22:23], 0, s[48:49]
	s_add_i32 s7, s6, 13
	s_add_i32 s8, s7, 1
	s_min_i32 s8, s8, 0x1000
	s_sub_i32 s46, s7, 1
	s_max_i32 s46, s46, 0
	s_sub_i32 s46, s8, s46
	v_cvt_f32_i32_e32 v220, s46
	v_rcp_f32_e32 v221, v220
	v_mul_f32_e32 v216, v4, v148
	v_mul_f32_e32 v217, v5, v149
	v_mul_f32_e32 v218, v6, v150
	v_mul_f32_e32 v219, v7, v151
	v_fma_f32 v222, -v220, v221, 1.0
	v_fma_f32 v221, v222, v221, v221
	v_fma_f32 v216, v8, v221, -v216
	v_fma_f32 v217, v9, v221, -v217
	v_fma_f32 v218, v10, v221, -v218
	v_fma_f32 v219, v11, v221, -v219
	v_cvt_pk_bf16_f32 v216, v216, v217
	v_cvt_pk_bf16_f32 v217, v218, v219
	global_store_dwordx2 v[22:23], v[216:217], off
	v_fma_f32 v8, -v4, v142, v8
	v_fma_f32 v9, -v5, v143, v9
	v_fma_f32 v10, -v6, v144, v10
	v_fma_f32 v11, -v7, v145, v11
	v_fma_f32 v8, v4, v152, v8
	v_fma_f32 v9, v5, v153, v9
	v_fma_f32 v10, v6, v154, v10
	v_fma_f32 v11, v7, v155, v11
	v_lshl_add_u64 v[22:23], v[22:23], 0, s[48:49]
	s_add_i32 s7, s6, 14
	s_add_i32 s8, s7, 1
	s_min_i32 s8, s8, 0x1000
	s_sub_i32 s46, s7, 1
	s_max_i32 s46, s46, 0
	s_sub_i32 s46, s8, s46
	v_cvt_f32_i32_e32 v220, s46
	v_rcp_f32_e32 v221, v220
	v_mul_f32_e32 v216, v4, v152
	v_mul_f32_e32 v217, v5, v153
	v_mul_f32_e32 v218, v6, v154
	v_mul_f32_e32 v219, v7, v155
	v_fma_f32 v222, -v220, v221, 1.0
	v_fma_f32 v221, v222, v221, v221
	v_fma_f32 v216, v8, v221, -v216
	v_fma_f32 v217, v9, v221, -v217
	v_fma_f32 v218, v10, v221, -v218
	v_fma_f32 v219, v11, v221, -v219
	v_cvt_pk_bf16_f32 v216, v216, v217
	v_cvt_pk_bf16_f32 v217, v218, v219
	global_store_dwordx2 v[22:23], v[216:217], off
	v_fma_f32 v8, -v4, v148, v8
	v_fma_f32 v9, -v5, v149, v9
	v_fma_f32 v10, -v6, v150, v10
	v_fma_f32 v11, -v7, v151, v11
	v_fma_f32 v8, v4, v156, v8
	v_fma_f32 v9, v5, v157, v9
	v_fma_f32 v10, v6, v158, v10
	v_fma_f32 v11, v7, v159, v11
	v_lshl_add_u64 v[22:23], v[22:23], 0, s[48:49]
	s_add_i32 s7, s6, 15
	s_add_i32 s8, s7, 1
	s_min_i32 s8, s8, 0x1000
	s_sub_i32 s46, s7, 1
	s_max_i32 s46, s46, 0
	s_sub_i32 s46, s8, s46
	v_cvt_f32_i32_e32 v220, s46
	v_rcp_f32_e32 v221, v220
	v_mul_f32_e32 v216, v4, v156
	v_mul_f32_e32 v217, v5, v157
	v_mul_f32_e32 v218, v6, v158
	v_mul_f32_e32 v219, v7, v159
	v_fma_f32 v222, -v220, v221, 1.0
	v_fma_f32 v221, v222, v221, v221
	v_fma_f32 v216, v8, v221, -v216
	v_fma_f32 v217, v9, v221, -v217
	v_fma_f32 v218, v10, v221, -v218
	v_fma_f32 v219, v11, v221, -v219
	v_cvt_pk_bf16_f32 v216, v216, v217
	v_cvt_pk_bf16_f32 v217, v218, v219
	global_store_dwordx2 v[22:23], v[216:217], off
	v_fma_f32 v8, -v4, v152, v8
	v_fma_f32 v9, -v5, v153, v9
	v_fma_f32 v10, -v6, v154, v10
	v_fma_f32 v11, -v7, v155, v11
	v_fma_f32 v8, v4, v160, v8
	v_fma_f32 v9, v5, v161, v9
	v_fma_f32 v10, v6, v162, v10
	v_fma_f32 v11, v7, v163, v11
	v_lshl_add_u64 v[22:23], v[22:23], 0, s[48:49]
.Lpp_next:
	s_add_i32 s5, s5, 1
	s_cmp_lt_u32 s5, 8
	s_cbranch_scc1 .Lpp_blk
	s_branch .LBB0_594

	.amdhsa_kernel _Z4mega6Params
		.amdhsa_group_segment_fixed_size 0
		.amdhsa_private_segment_fixed_size 0
		.amdhsa_kernarg_size 528
		.amdhsa_user_sgpr_count 2
		.amdhsa_user_sgpr_dispatch_ptr 0
		.amdhsa_user_sgpr_queue_ptr 0
		.amdhsa_user_sgpr_kernarg_segment_ptr 1
		.amdhsa_user_sgpr_dispatch_id 0
		.amdhsa_user_sgpr_kernarg_preload_length 0
		.amdhsa_user_sgpr_kernarg_preload_offset 0
		.amdhsa_user_sgpr_private_segment_size 0
		.amdhsa_uses_dynamic_stack 0
		.amdhsa_enable_private_segment 0
		.amdhsa_system_sgpr_workgroup_id_x 1
		.amdhsa_system_sgpr_workgroup_id_y 0
		.amdhsa_system_sgpr_workgroup_id_z 0
		.amdhsa_system_sgpr_workgroup_info 0
		.amdhsa_system_vgpr_workitem_id 2
		.amdhsa_next_free_vgpr 256
		.amdhsa_next_free_sgpr 102
		.amdhsa_accum_offset 256
		.amdhsa_reserve_vcc 1
		.amdhsa_float_round_mode_32 0
		.amdhsa_float_round_mode_16_64 0
		.amdhsa_float_denorm_mode_32 3
		.amdhsa_float_denorm_mode_16_64 3
		.amdhsa_dx10_clamp 1
		.amdhsa_ieee_mode 1
		.amdhsa_fp16_overflow 0
		.amdhsa_tg_split 0
		.amdhsa_exception_fp_ieee_invalid_op 0
		.amdhsa_exception_fp_denorm_src 0
		.amdhsa_exception_fp_ieee_div_zero 0
		.amdhsa_exception_fp_ieee_overflow 0
		.amdhsa_exception_fp_ieee_underflow 0
		.amdhsa_exception_fp_ieee_inexact 0
		.amdhsa_exception_int_div_zero 0
	.end_amdhsa_kernel

amdhsa.kernels:
  - .agpr_count:     0
    .args:
      - .offset:         0
        .size:           272
        .value_kind:     by_value
      - .offset:         272
        .size:           4
        .value_kind:     hidden_block_count_x
      - .offset:         276
        .size:           4
        .value_kind:     hidden_block_count_y
      - .offset:         280
        .size:           4
        .value_kind:     hidden_block_count_z
      - .offset:         284
        .size:           2
        .value_kind:     hidden_group_size_x
      - .offset:         286
        .size:           2
        .value_kind:     hidden_group_size_y
      - .offset:         288
        .size:           2
        .value_kind:     hidden_group_size_z
      - .offset:         290
        .size:           2
        .value_kind:     hidden_remainder_x
      - .offset:         292
        .size:           2
        .value_kind:     hidden_remainder_y
      - .offset:         294
        .size:           2
        .value_kind:     hidden_remainder_z
      - .offset:         312
        .size:           8
        .value_kind:     hidden_global_offset_x
      - .offset:         320
        .size:           8
        .value_kind:     hidden_global_offset_y
      - .offset:         328
        .size:           8
        .value_kind:     hidden_global_offset_z
      - .offset:         336
        .size:           2
        .value_kind:     hidden_grid_dims
      - .offset:         360
        .size:           8
        .value_kind:     hidden_multigrid_sync_arg
      - .offset:         392
        .size:           4
        .value_kind:     hidden_dynamic_lds_size
    .group_segment_fixed_size: 0
    .kernarg_segment_align: 8
    .kernarg_segment_size: 528
    .language:       OpenCL C
    .language_version:
      - 2
      - 0
    .max_flat_workgroup_size: 512
    .name:           _Z4mega6Params
    .private_segment_fixed_size: 0
    .sgpr_count:     108
    .sgpr_spill_count: 100
    .symbol:         _Z4mega6Params.kd
    .uniform_work_group_size: 1
    .uses_dynamic_stack: false
    .vgpr_count:     256
    .vgpr_spill_count: 0
    .wavefront_size: 64
